# hgm12 + saddr LDS-DMA addressing at 92 of 96 K-loop sites (adds loop-invariant A sites and the out-projection loop)
# speedup vs baseline: 1.0355x; 1.0060x over previous
.LBB0_247:
	s_add_u32 s98, s34, s52
	s_addc_u32 s99, s35, s53
	s_add_u32 s33, s34, s52
	s_addc_u32 s58, s35, s53
	s_add_u32 s33, s33, 0x100
	s_addc_u32 s60, s58, 0
	ds_read_b128 v[156:159], v152
	ds_read_b128 v[160:163], v152 offset:1024
	ds_read_b128 v[164:167], v152 offset:2048
	ds_read_b128 v[168:171], v152 offset:3072
	ds_read_b128 v[172:175], v153
	ds_read_b128 v[176:179], v153 offset:1024
	ds_read_b128 v[180:183], v153 offset:2048
	ds_read_b128 v[184:187], v153 offset:3072
	s_add_u32 s94, s91, s52
	s_addc_u32 s95, s92, s53
	s_cmp_eq_u32 s52, 0
	s_cselect_b64 s[58:59], -1, 0
	s_and_b64 s[58:59], s[36:37], s[58:59]
	s_cmpk_eq_i32 s52, 0x700
	v_cndmask_b32_e64 v155, 0, 1, s[58:59]
	s_cselect_b32 s61, s19, s60
	s_cselect_b32 s60, s85, s33
	v_readfirstlane_b32 s33, v155
	s_cselect_b32 s59, s17, s95
	s_cselect_b32 s58, s88, s94
	s_add_i32 m0, s31, 0xc000
	ds_read_b128 v[188:191], v154
	ds_read_b128 v[192:195], v154 offset:1024
	ds_read_b128 v[196:199], v154 offset:2048
	ds_read_b128 v[200:203], v154 offset:3072
	ds_read_b128 v[204:207], v154 offset:4096
	ds_read_b128 v[212:215], v154 offset:5120
	ds_read_b128 v[216:219], v154 offset:6144
	ds_read_b128 v[220:223], v154 offset:7168
	global_load_lds_dwordx4 v138, s[98:99]
	s_add_i32 m0, s31, 0xe000
	s_and_b32 s33, s33, 1
	global_load_lds_dwordx4 v140, s[98:99]
	s_cmp_lg_u32 s33, 0
	s_cbranch_scc1 .Lpg8skip0
	s_waitcnt vmcnt(8)

.LBB0_947:
	s_add_u32 s98, s6, s36
	s_addc_u32 s99, s7, s37
	v_add_u32_e32 v1, s78, v201
	ds_read_b128 v[132:135], v1
	ds_read_b128 v[136:139], v1 offset:1024
	ds_read_b128 v[144:147], v1 offset:2048
	ds_read_b128 v[164:167], v1 offset:3072
	v_add_u32_e32 v1, s79, v201
	s_add_u32 s0, s6, s36
	ds_read_b128 v[168:171], v1
	ds_read_b128 v[172:175], v1 offset:1024
	ds_read_b128 v[176:179], v1 offset:2048
	ds_read_b128 v[180:183], v1 offset:3072
	s_addc_u32 s1, s7, s37
	s_add_u32 s0, s0, 0x100
	s_addc_u32 s1, s1, 0
	s_add_u32 s33, s92, s36
	s_addc_u32 s68, s93, s37
	s_cmpk_eq_i32 s36, 0x700
	s_cselect_b32 s43, s25, s1
	s_cselect_b32 s42, s31, s0
	s_cselect_b32 s1, s35, s68
	s_cselect_b32 s0, s82, s33
	s_add_i32 m0, s49, 0xc000
	ds_read_b128 v[184:187], v204
	ds_read_b128 v[188:191], v204 offset:1024
	ds_read_b128 v[192:195], v204 offset:2048
	ds_read_b128 v[206:209], v204 offset:3072
	ds_read_b128 v[212:215], v204 offset:4096
	ds_read_b128 v[216:219], v204 offset:5120
	ds_read_b128 v[220:223], v204 offset:6144
	ds_read_b128 v[224:227], v204 offset:7168
	global_load_lds_dwordx4 v156, s[98:99]
	s_add_i32 m0, s49, 0xe000
	s_nop 0
	global_load_lds_dwordx4 v158, s[98:99]
	s_cmp_lg_u32 s80, 0
	s_cbranch_scc1 .Lpg8skip6
	s_waitcnt vmcnt(8)
.Lpg8skip6:
	s_waitcnt lgkmcnt(0)
	s_barrier
	s_setprio 1
	s_waitcnt lgkmcnt(0)
	v_mfma_f32_16x16x32_bf16 v[120:123], v[132:135], v[184:187], v[120:123]
	v_mfma_f32_16x16x32_bf16 v[128:131], v[144:147], v[184:187], v[128:131]
	v_mfma_f32_16x16x32_bf16 v[112:115], v[132:135], v[192:195], v[112:115]
	v_mfma_f32_16x16x32_bf16 v[108:111], v[144:147], v[192:195], v[108:111]
	v_mfma_f32_16x16x32_bf16 v[96:99], v[132:135], v[212:215], v[96:99]
	v_mfma_f32_16x16x32_bf16 v[92:95], v[144:147], v[212:215], v[92:95]
	v_mfma_f32_16x16x32_bf16 v[80:83], v[132:135], v[220:223], v[80:83]
	v_mfma_f32_16x16x32_bf16 v[76:79], v[144:147], v[220:223], v[76:79]
	v_mfma_f32_16x16x32_bf16 v[120:123], v[136:139], v[188:191], v[120:123]
	v_mfma_f32_16x16x32_bf16 v[128:131], v[164:167], v[188:191], v[128:131]
	v_mfma_f32_16x16x32_bf16 v[112:115], v[136:139], v[206:209], v[112:115]
	v_mfma_f32_16x16x32_bf16 v[108:111], v[164:167], v[206:209], v[108:111]
	v_mfma_f32_16x16x32_bf16 v[96:99], v[136:139], v[216:219], v[96:99]
	v_mfma_f32_16x16x32_bf16 v[92:95], v[164:167], v[216:219], v[92:95]
	v_mfma_f32_16x16x32_bf16 v[80:83], v[136:139], v[224:227], v[80:83]
	v_mfma_f32_16x16x32_bf16 v[76:79], v[164:167], v[224:227], v[76:79]
	s_setprio 0
	s_setprio 1
	v_mfma_f32_16x16x32_bf16 v[124:127], v[168:171], v[184:187], v[124:127]
	v_mfma_f32_16x16x32_bf16 v[116:119], v[176:179], v[184:187], v[116:119]
	v_mfma_f32_16x16x32_bf16 v[104:107], v[168:171], v[192:195], v[104:107]
	v_mfma_f32_16x16x32_bf16 v[100:103], v[176:179], v[192:195], v[100:103]
	v_mfma_f32_16x16x32_bf16 v[88:91], v[168:171], v[212:215], v[88:91]
	v_mfma_f32_16x16x32_bf16 v[84:87], v[176:179], v[212:215], v[84:87]
	v_mfma_f32_16x16x32_bf16 v[72:75], v[168:171], v[220:223], v[72:75]
	v_mfma_f32_16x16x32_bf16 v[68:71], v[176:179], v[220:223], v[68:71]
	v_mfma_f32_16x16x32_bf16 v[124:127], v[172:175], v[188:191], v[124:127]
	v_mfma_f32_16x16x32_bf16 v[116:119], v[180:183], v[188:191], v[116:119]
	v_mfma_f32_16x16x32_bf16 v[104:107], v[172:175], v[206:209], v[104:107]
	v_mfma_f32_16x16x32_bf16 v[100:103], v[180:183], v[206:209], v[100:103]
	v_mfma_f32_16x16x32_bf16 v[88:91], v[172:175], v[216:219], v[88:91]
	v_mfma_f32_16x16x32_bf16 v[84:87], v[180:183], v[216:219], v[84:87]
	v_mfma_f32_16x16x32_bf16 v[72:75], v[172:175], v[224:227], v[72:75]
	v_mfma_f32_16x16x32_bf16 v[68:71], v[180:183], v[224:227], v[68:71]
	s_setprio 0
	s_barrier
	s_add_i32 s33, s78, s48
	s_add_u32 s98, s0, s14
	s_addc_u32 s99, s1, s15
	s_mov_b32 m0, s33
	ds_read_b128 v[184:187], v204 offset:16384
	ds_read_b128 v[188:191], v204 offset:17408
	ds_read_b128 v[192:195], v204 offset:18432
	ds_read_b128 v[206:209], v204 offset:19456
	ds_read_b128 v[212:215], v204 offset:20480
	ds_read_b128 v[216:219], v204 offset:21504
	ds_read_b128 v[220:223], v204 offset:22528
	ds_read_b128 v[224:227], v204 offset:23552
	global_load_lds_dwordx4 v150, s[0:1]
	s_add_i32 m0, s33, 0x2000
	s_add_u32 s68, s0, 0x40000
	s_addc_u32 s69, s1, 0
	s_add_i32 s33, s79, s48
	global_load_lds_dwordx4 v154, s[0:1]
	s_mov_b32 m0, s33
	s_add_u32 s100, s42, s14
	s_addc_u32 s101, s43, s15
	global_load_lds_dwordx4 v150, s[68:69]
	s_add_i32 m0, s33, 0x2000
	s_nop 0
	global_load_lds_dwordx4 v154, s[68:69]
	s_mov_b32 m0, s49
	s_mov_b32 s33, 0
	global_load_lds_dwordx4 v148, s[42:43]
	s_mov_b32 m0, s50
	s_nop 0
	global_load_lds_dwordx4 v152, s[42:43]
	s_cmp_lg_u32 s33, 0
	s_cbranch_scc1 .Lpg8skip7
	s_waitcnt vmcnt(8)
.Lpg8skip7:
	s_waitcnt lgkmcnt(0)
	s_barrier
	s_setprio 1
	s_waitcnt lgkmcnt(0)
	v_mfma_f32_16x16x32_bf16 v[64:67], v[132:135], v[184:187], v[64:67]
	v_mfma_f32_16x16x32_bf16 v[60:63], v[144:147], v[184:187], v[60:63]
	v_mfma_f32_16x16x32_bf16 v[48:51], v[132:135], v[192:195], v[48:51]
	v_mfma_f32_16x16x32_bf16 v[44:47], v[144:147], v[192:195], v[44:47]
	v_mfma_f32_16x16x32_bf16 v[32:35], v[132:135], v[212:215], v[32:35]
	v_mfma_f32_16x16x32_bf16 v[28:31], v[144:147], v[212:215], v[28:31]
	v_mfma_f32_16x16x32_bf16 v[16:19], v[132:135], v[220:223], v[16:19]
	v_mfma_f32_16x16x32_bf16 v[12:15], v[144:147], v[220:223], v[12:15]
	v_mfma_f32_16x16x32_bf16 v[64:67], v[136:139], v[188:191], v[64:67]
	v_mfma_f32_16x16x32_bf16 v[60:63], v[164:167], v[188:191], v[60:63]
	v_mfma_f32_16x16x32_bf16 v[48:51], v[136:139], v[206:209], v[48:51]
	v_mfma_f32_16x16x32_bf16 v[44:47], v[164:167], v[206:209], v[44:47]
	v_mfma_f32_16x16x32_bf16 v[32:35], v[136:139], v[216:219], v[32:35]
	v_mfma_f32_16x16x32_bf16 v[28:31], v[164:167], v[216:219], v[28:31]
	v_mfma_f32_16x16x32_bf16 v[16:19], v[136:139], v[224:227], v[16:19]
	v_mfma_f32_16x16x32_bf16 v[12:15], v[164:167], v[224:227], v[12:15]
	s_setprio 0
	s_setprio 1
	v_mfma_f32_16x16x32_bf16 v[56:59], v[168:171], v[184:187], v[56:59]
	v_mfma_f32_16x16x32_bf16 v[52:55], v[176:179], v[184:187], v[52:55]
	v_mfma_f32_16x16x32_bf16 v[40:43], v[168:171], v[192:195], v[40:43]
	v_mfma_f32_16x16x32_bf16 v[36:39], v[176:179], v[192:195], v[36:39]
	v_mfma_f32_16x16x32_bf16 v[24:27], v[168:171], v[212:215], v[24:27]
	v_mfma_f32_16x16x32_bf16 v[20:23], v[176:179], v[212:215], v[20:23]
	v_mfma_f32_16x16x32_bf16 v[8:11], v[168:171], v[220:223], v[8:11]
	v_mfma_f32_16x16x32_bf16 v[2:5], v[176:179], v[220:223], v[4:7]
	v_mfma_f32_16x16x32_bf16 v[56:59], v[172:175], v[188:191], v[56:59]
	v_mfma_f32_16x16x32_bf16 v[52:55], v[180:183], v[188:191], v[52:55]
	v_mfma_f32_16x16x32_bf16 v[40:43], v[172:175], v[206:209], v[40:43]
	v_mfma_f32_16x16x32_bf16 v[36:39], v[180:183], v[206:209], v[36:39]
	v_mfma_f32_16x16x32_bf16 v[24:27], v[172:175], v[216:219], v[24:27]
	v_mfma_f32_16x16x32_bf16 v[20:23], v[180:183], v[216:219], v[20:23]
	v_mfma_f32_16x16x32_bf16 v[8:11], v[172:175], v[224:227], v[8:11]
	v_mfma_f32_16x16x32_bf16 v[2:5], v[180:183], v[224:227], v[2:5]
	s_setprio 0
	s_barrier
	s_add_i32 s33, 0, 0x18000
	v_add_u32_e32 v1, s33, v201
	s_add_i32 s68, 0, 0x1c000
	ds_read_b128 v[132:135], v1
	ds_read_b128 v[136:139], v1 offset:1024
	ds_read_b128 v[144:147], v1 offset:2048
	ds_read_b128 v[164:167], v1 offset:3072
	v_add_u32_e32 v1, s68, v201
	ds_read_b128 v[168:171], v1
	ds_read_b128 v[172:175], v1 offset:1024
	ds_read_b128 v[176:179], v1 offset:2048
	ds_read_b128 v[180:183], v1 offset:3072
	s_add_u32 s42, s42, 0x40000
	s_addc_u32 s43, s43, 0
	s_mov_b32 m0, s51
	ds_read_b128 v[184:187], v204 offset:32768
	ds_read_b128 v[188:191], v204 offset:33792
	ds_read_b128 v[192:195], v204 offset:34816
	ds_read_b128 v[206:209], v204 offset:35840
	ds_read_b128 v[212:215], v204 offset:36864
	ds_read_b128 v[216:219], v204 offset:37888
	ds_read_b128 v[220:223], v204 offset:38912
	ds_read_b128 v[224:227], v204 offset:39936
	global_load_lds_dwordx4 v148, s[42:43]
	s_mov_b32 m0, s52
	s_nop 0
	global_load_lds_dwordx4 v152, s[42:43]
	s_waitcnt vmcnt(8)
	s_waitcnt lgkmcnt(0)
	s_barrier
	s_setprio 1
	s_waitcnt lgkmcnt(0)
	v_mfma_f32_16x16x32_bf16 v[120:123], v[132:135], v[184:187], v[120:123]
	v_mfma_f32_16x16x32_bf16 v[128:131], v[144:147], v[184:187], v[128:131]
	v_mfma_f32_16x16x32_bf16 v[112:115], v[132:135], v[192:195], v[112:115]
	v_mfma_f32_16x16x32_bf16 v[108:111], v[144:147], v[192:195], v[108:111]
	v_mfma_f32_16x16x32_bf16 v[96:99], v[132:135], v[212:215], v[96:99]
	v_mfma_f32_16x16x32_bf16 v[92:95], v[144:147], v[212:215], v[92:95]
	v_mfma_f32_16x16x32_bf16 v[80:83], v[132:135], v[220:223], v[80:83]
	v_mfma_f32_16x16x32_bf16 v[76:79], v[144:147], v[220:223], v[76:79]
	v_mfma_f32_16x16x32_bf16 v[120:123], v[136:139], v[188:191], v[120:123]
	v_mfma_f32_16x16x32_bf16 v[128:131], v[164:167], v[188:191], v[128:131]
	v_mfma_f32_16x16x32_bf16 v[112:115], v[136:139], v[206:209], v[112:115]
	v_mfma_f32_16x16x32_bf16 v[108:111], v[164:167], v[206:209], v[108:111]
	v_mfma_f32_16x16x32_bf16 v[96:99], v[136:139], v[216:219], v[96:99]
	v_mfma_f32_16x16x32_bf16 v[92:95], v[164:167], v[216:219], v[92:95]
	v_mfma_f32_16x16x32_bf16 v[80:83], v[136:139], v[224:227], v[80:83]
	v_mfma_f32_16x16x32_bf16 v[76:79], v[164:167], v[224:227], v[76:79]
	s_setprio 0
	s_setprio 1
	v_mfma_f32_16x16x32_bf16 v[124:127], v[168:171], v[184:187], v[124:127]
	v_mfma_f32_16x16x32_bf16 v[116:119], v[176:179], v[184:187], v[116:119]
	v_mfma_f32_16x16x32_bf16 v[104:107], v[168:171], v[192:195], v[104:107]
	v_mfma_f32_16x16x32_bf16 v[100:103], v[176:179], v[192:195], v[100:103]
	v_mfma_f32_16x16x32_bf16 v[88:91], v[168:171], v[212:215], v[88:91]
	v_mfma_f32_16x16x32_bf16 v[84:87], v[176:179], v[212:215], v[84:87]
	v_mfma_f32_16x16x32_bf16 v[72:75], v[168:171], v[220:223], v[72:75]
	v_mfma_f32_16x16x32_bf16 v[68:71], v[176:179], v[220:223], v[68:71]
	v_mfma_f32_16x16x32_bf16 v[124:127], v[172:175], v[188:191], v[124:127]
	v_mfma_f32_16x16x32_bf16 v[116:119], v[180:183], v[188:191], v[116:119]
	v_mfma_f32_16x16x32_bf16 v[104:107], v[172:175], v[206:209], v[104:107]
	v_mfma_f32_16x16x32_bf16 v[100:103], v[180:183], v[206:209], v[100:103]
	v_mfma_f32_16x16x32_bf16 v[88:91], v[172:175], v[216:219], v[88:91]
	v_mfma_f32_16x16x32_bf16 v[84:87], v[180:183], v[216:219], v[84:87]
	v_mfma_f32_16x16x32_bf16 v[72:75], v[172:175], v[224:227], v[72:75]
	v_mfma_f32_16x16x32_bf16 v[68:71], v[180:183], v[224:227], v[68:71]
	s_setprio 0
	s_barrier
	s_add_i32 s33, s33, s48
	s_mov_b32 m0, s33
	ds_read_b128 v[184:187], v204 offset:49152
	ds_read_b128 v[188:191], v204 offset:50176
	ds_read_b128 v[192:195], v204 offset:51200
	ds_read_b128 v[206:209], v204 offset:52224
	ds_read_b128 v[212:215], v204 offset:53248
	ds_read_b128 v[216:219], v204 offset:54272
	ds_read_b128 v[220:223], v204 offset:55296
	ds_read_b128 v[224:227], v204 offset:56320
	global_load_lds_dwordx4 v150, s[98:99]
	s_add_i32 m0, s33, 0x2000
	s_add_u32 s0, s0, 0x40080
	s_addc_u32 s1, s1, 0
	s_add_i32 s33, s68, s48
	global_load_lds_dwordx4 v154, s[98:99]
	s_mov_b32 m0, s33
	s_nop 0
	global_load_lds_dwordx4 v150, s[0:1]
	s_add_i32 m0, s33, 0x2000
	s_nop 0
	global_load_lds_dwordx4 v154, s[0:1]
	s_mov_b32 m0, s71
	s_nop 0
	global_load_lds_dwordx4 v148, s[100:101]
	s_mov_b32 m0, s72
	s_nop 0
	global_load_lds_dwordx4 v152, s[100:101]
	s_waitcnt vmcnt(8)
	s_waitcnt lgkmcnt(0)
	s_barrier
	s_setprio 1
	s_waitcnt lgkmcnt(0)
	v_mfma_f32_16x16x32_bf16 v[64:67], v[132:135], v[184:187], v[64:67]
	v_mfma_f32_16x16x32_bf16 v[60:63], v[144:147], v[184:187], v[60:63]
	v_mfma_f32_16x16x32_bf16 v[48:51], v[132:135], v[192:195], v[48:51]
	v_mfma_f32_16x16x32_bf16 v[44:47], v[144:147], v[192:195], v[44:47]
	v_mfma_f32_16x16x32_bf16 v[32:35], v[132:135], v[212:215], v[32:35]
	v_mfma_f32_16x16x32_bf16 v[28:31], v[144:147], v[212:215], v[28:31]
	v_mfma_f32_16x16x32_bf16 v[16:19], v[132:135], v[220:223], v[16:19]
	v_mfma_f32_16x16x32_bf16 v[12:15], v[144:147], v[220:223], v[12:15]
	v_mfma_f32_16x16x32_bf16 v[64:67], v[136:139], v[188:191], v[64:67]
	v_mfma_f32_16x16x32_bf16 v[60:63], v[164:167], v[188:191], v[60:63]
	v_mfma_f32_16x16x32_bf16 v[48:51], v[136:139], v[206:209], v[48:51]
	v_mfma_f32_16x16x32_bf16 v[44:47], v[164:167], v[206:209], v[44:47]
	v_mfma_f32_16x16x32_bf16 v[32:35], v[136:139], v[216:219], v[32:35]
	v_mfma_f32_16x16x32_bf16 v[28:31], v[164:167], v[216:219], v[28:31]
	v_mfma_f32_16x16x32_bf16 v[16:19], v[136:139], v[224:227], v[16:19]
	v_mfma_f32_16x16x32_bf16 v[12:15], v[164:167], v[224:227], v[12:15]
	s_setprio 0
	s_setprio 1
	v_mfma_f32_16x16x32_bf16 v[56:59], v[168:171], v[184:187], v[56:59]
	v_mfma_f32_16x16x32_bf16 v[52:55], v[176:179], v[184:187], v[52:55]
	v_mfma_f32_16x16x32_bf16 v[40:43], v[168:171], v[192:195], v[40:43]
	v_mfma_f32_16x16x32_bf16 v[36:39], v[176:179], v[192:195], v[36:39]
	v_mfma_f32_16x16x32_bf16 v[24:27], v[168:171], v[212:215], v[24:27]
	v_mfma_f32_16x16x32_bf16 v[20:23], v[176:179], v[212:215], v[20:23]
	v_mfma_f32_16x16x32_bf16 v[6:9], v[168:171], v[220:223], v[8:11]
	v_mfma_f32_16x16x32_bf16 v[2:5], v[176:179], v[220:223], v[2:5]
	v_mfma_f32_16x16x32_bf16 v[56:59], v[172:175], v[188:191], v[56:59]
	v_mfma_f32_16x16x32_bf16 v[52:55], v[180:183], v[188:191], v[52:55]
	v_mfma_f32_16x16x32_bf16 v[40:43], v[172:175], v[206:209], v[40:43]
	v_mfma_f32_16x16x32_bf16 v[36:39], v[180:183], v[206:209], v[36:39]
	v_mfma_f32_16x16x32_bf16 v[24:27], v[172:175], v[216:219], v[24:27]
	v_mfma_f32_16x16x32_bf16 v[20:23], v[180:183], v[216:219], v[20:23]
	v_mfma_f32_16x16x32_bf16 v[8:11], v[172:175], v[224:227], v[6:9]
	v_mfma_f32_16x16x32_bf16 v[4:7], v[180:183], v[224:227], v[2:5]
	s_setprio 0
	s_barrier
	s_add_i32 s94, s94, 2
	s_add_u32 s36, s36, 0x100
	s_addc_u32 s37, s37, 0
	s_cmp_gt_u32 s94, 13
	s_cbranch_scc1 .LBB0_950

.LBB0_1047:
	s_add_u32 s98, s26, s30
	s_addc_u32 s99, s27, s31
	ds_read_b128 v[156:159], v152
	ds_read_b128 v[160:163], v152 offset:1024
	ds_read_b128 v[164:167], v152 offset:2048
	ds_read_b128 v[168:171], v152 offset:3072
	ds_read_b128 v[172:175], v153
	ds_read_b128 v[176:179], v153 offset:1024
	ds_read_b128 v[180:183], v153 offset:2048
	ds_read_b128 v[184:187], v153 offset:3072
	s_add_u32 s33, s26, s30
	s_addc_u32 s34, s27, s31
	s_add_u32 s33, s33, 0x100
	s_addc_u32 s36, s34, 0
	s_add_u32 s75, s72, s30
	s_addc_u32 s76, s73, s31
	s_cmp_eq_u32 s30, 0
	s_cselect_b64 s[34:35], -1, 0
	s_and_b64 s[34:35], s[28:29], s[34:35]
	s_cmpk_eq_i32 s30, 0x700
	v_cndmask_b32_e64 v155, 0, 1, s[34:35]
	s_cselect_b32 s37, s19, s36
	s_cselect_b32 s36, s70, s33
	v_readfirstlane_b32 s33, v155
	s_cselect_b32 s35, s17, s76
	s_cselect_b32 s34, s71, s75
	s_add_i32 m0, s25, 0xc000
	ds_read_b128 v[188:191], v154
	ds_read_b128 v[192:195], v154 offset:1024
	ds_read_b128 v[196:199], v154 offset:2048
	ds_read_b128 v[200:203], v154 offset:3072
	ds_read_b128 v[204:207], v154 offset:4096
	ds_read_b128 v[212:215], v154 offset:5120
	ds_read_b128 v[216:219], v154 offset:6144
	ds_read_b128 v[220:223], v154 offset:7168
	global_load_lds_dwordx4 v138, s[98:99]
	s_add_i32 m0, s25, 0xe000
	s_and_b32 s33, s33, 1
	global_load_lds_dwordx4 v140, s[98:99]
	s_cmp_lg_u32 s33, 0
	s_cbranch_scc1 .Lpg8skip8
	s_waitcnt vmcnt(8)
